# MLA unit prologue: first K/V LDS-DMA tiles issued without waiting for the q-fragment loads (one exposed round trip less per unit); on top of phase-4 rebalance v2
# baseline (speedup 1.0000x reference)
; template <int DQK> __device__ __forceinline__ int kswz(int row, int colB) { return row * (DQK * 2) + (colB ^ kswz_x<DQK>(row)); }
; __device__ __forceinline__ int v_rd_base(int lane) { return ((lane & 3) << 3) | (((lane >> 2) & 3) << 6) | (((lane >> 4) & 1) << 5) | (((lane >> 5) & 1) << 8); }
; template <int MODE>
; __device__ __forceinline__ void attn_unit(unsigned char* ws_, const float* rpb, const float* sink, int l, int h, int qb, int kvq, unsigned char* lds_g) {
;     ...
;   { const bf16_t* Qw = Qp + (size_t)qi * ldq + hi * 8;
; #pragma unroll
;     for (int d0 = 0; d0 < ND; ++d0) qr[d0] = *(const bf16x8*)(Qw + d0 * 16); }
;   unsigned kg[NCH], vg[2];
; #pragma unroll
;   for (int i = 0; i < NCH; ++i) { const int X = (wid + 8 * i) * 1024 + lane * 16, row = X / (DQK * 2), cs = X % (DQK * 2), colB = cs ^ kswz_x<DQK>(row); kg[i] = (unsigned)(row * ldk + (colB >> 1)) * 2u; }
; #pragma unroll
;   for (int i = 0; i < 2; ++i) { const int X = (wid + 8 * i) * 1024 + lane * 16, st = X >> 9, w = X & 511, kk = ((st >> 2) << 3) | (w >> 6), c = ((st & 3) << 5) | ((w & 63) >> 1);
;     const int k = kk;
;     vg[i] = (unsigned)(k * ldv + c) * 2u; }
;   const int vb0 = (int)(uintptr_t)lds_g + v_rd_base(lane);
;   const int kbase0 = (int)(uintptr_t)lds_g + OFF_K;
;   constexpr int NKO = DQK == 192 ? 4 : ND;
;   int ko[NKO];
; #pragma unroll
;   for (int d0 = 0; d0 < NKO; ++d0) ko[d0] = kswz<DQK>(r32, (d0 * 16 + hi * 8) * 2);
;     ...
;   const int wslab = __builtin_amdgcn_readfirstlane(wid) * 1024;
;     ...
;   __syncthreads();
;   ATT_DMA(T0, 0); if (T0 + 1 < T1) { ATT_DMA(T0 + 1, 1); asm volatile("s_waitcnt vmcnt(%0)" :: "n"(NCH + 2) : "memory"); } else asm volatile("s_waitcnt vmcnt(0)" ::: "memory");
.LBB0_864:
	v_mov_b32_e32 v0, s28
	ds_read_b64 v[2:3], v0
	s_ashr_i32 s15, s5, 2
	s_mul_i32 s6, s15, 0xc0
	s_ashr_i32 s7, s6, 31
	s_and_b32 s14, s5, 3
	s_waitcnt lgkmcnt(0)
	v_readfirstlane_b32 s2, v2
	s_lshl_b64 s[8:9], s[6:7], 1
	v_readfirstlane_b32 s3, v3
	s_add_u32 s5, s2, s8
	s_addc_u32 s6, s3, s9
	s_add_u32 s10, s5, 0x15428000
	s_addc_u32 s11, s6, 0
	v_mov_b32_e32 v5, v216
	s_add_u32 s21, s5, 0x16828000
	s_addc_u32 s22, s6, 0
	v_ashrrev_i32_e32 v7, 6, v5
	s_lshl_b32 s4, s4, 8
	s_and_b32 s16, s4, 0x1f00
	v_lshlrev_b32_e32 v179, 5, v7
	v_and_b32_e32 v177, 31, v5
	v_add_u32_e32 v0, s16, v179
	v_or_b32_e32 v146, v0, v177
	v_and_b32_e32 v0, 0x3fffffc0, v5
	s_add_i32 s4, 0, 0x1e000
	v_bfe_u32 v176, v5, 5, 1
	v_lshl_add_u32 v178, v0, 2, s4
	v_mov_b64_e32 v[2:3], s[10:11]
	s_movk_i32 s4, 0xa00
	v_mad_i64_i32 v[2:3], s[4:5], v146, s4, v[2:3]
	v_lshlrev_b32_e32 v0, 4, v176
	v_and_b32_e32 v8, 63, v5
	v_lshl_add_u64 v[2:3], v[2:3], 0, v[0:1]
	flat_load_dwordx4 v[98:101], v[2:3]
	flat_load_dwordx4 v[102:105], v[2:3] offset:32
	flat_load_dwordx4 v[106:109], v[2:3] offset:64
	flat_load_dwordx4 v[110:113], v[2:3] offset:96
	flat_load_dwordx4 v[114:117], v[2:3] offset:128
	flat_load_dwordx4 v[118:121], v[2:3] offset:160
	flat_load_dwordx4 v[122:125], v[2:3] offset:192
	flat_load_dwordx4 v[126:129], v[2:3] offset:224
	flat_load_dwordx4 v[130:133], v[2:3] offset:256
	flat_load_dwordx4 v[134:137], v[2:3] offset:288
	flat_load_dwordx4 v[138:141], v[2:3] offset:320
	flat_load_dwordx4 v[142:145], v[2:3] offset:352
	v_lshlrev_b32_e32 v3, 10, v7
	v_lshlrev_b32_e32 v9, 4, v8
	v_or_b32_e32 v6, v3, v9
	v_mul_hi_i32 v2, v6, s29
	v_lshrrev_b32_e32 v4, 31, v2
	v_ashrrev_i32_e32 v2, 6, v2
	v_add_u32_e32 v2, v2, v4
	v_mul_i32_i24_e32 v4, 0x180, v2
	v_lshlrev_b32_e32 v10, 3, v2
	v_sub_u32_e32 v4, v6, v4
	v_and_b32_e32 v10, 0x70, v10
	v_mul_i32_i24_e32 v2, 0x900, v2
	v_xad_u32 v2, v10, v4, v2
	v_add_u32_e32 v4, 0x2000, v6
	v_mul_hi_i32 v10, v4, s29
	v_lshrrev_b32_e32 v11, 31, v10
	v_ashrrev_i32_e32 v10, 6, v10
	v_add_u32_e32 v10, v10, v11
	v_mul_i32_i24_e32 v11, 0x180, v10
	v_sub_u32_e32 v4, v4, v11
	v_lshlrev_b32_e32 v11, 3, v10
	v_and_b32_e32 v11, 0x70, v11
	v_mul_i32_i24_e32 v10, 0x900, v10
	v_add_u32_e32 v6, 0x4000, v6
	v_xad_u32 v4, v11, v4, v10
	v_mul_hi_i32 v10, v6, s29
	s_lshl_b32 s6, s15, 7
	v_lshrrev_b32_e32 v11, 31, v10
	v_ashrrev_i32_e32 v10, 6, v10
	s_ashr_i32 s7, s6, 31
	s_lshl_b32 s18, s14, 5
	v_add_u32_e32 v10, v10, v11
	s_add_i32 s19, s18, 32
	v_mul_i32_i24_e32 v11, 0x180, v10
	s_lshl_b64 s[10:11], s[6:7], 1
	v_sub_u32_e32 v6, v6, v11
	v_lshlrev_b32_e32 v11, 3, v10
	s_add_u32 s4, s2, s10
	v_and_b32_e32 v11, 0x70, v11
	v_mul_i32_i24_e32 v10, 0x900, v10
	s_addc_u32 s5, s3, s11
	v_ashrrev_i32_e32 v16, 8, v3
	v_add_u32_e32 v3, 0x2000, v3
	v_xad_u32 v6, v11, v6, v10
	s_add_u32 s23, s4, 0x17a28000
	v_bfe_u32 v11, v5, 2, 3
	s_mov_b32 s4, 0xfffff8
	v_ashrrev_i32_e32 v18, 8, v3
	v_and_or_b32 v17, v16, s4, v11
	v_and_or_b32 v3, v18, s4, v11
	v_readfirstlane_b32 s4, v7
	s_addc_u32 s24, s5, 0
	s_lshl_b32 s20, s4, 10
	s_lshl_b32 s25, s14, 11
	s_mul_i32 s26, s14, 0x480000
	s_add_u32 s4, s21, s26
	s_addc_u32 s5, s22, 0
	s_add_i32 s20, s20, 0
	v_lshlrev_b32_e32 v10, 3, v8
	s_add_i32 m0, s20, 0xc000
	v_and_b32_e32 v12, 32, v5
	v_and_b32_e32 v13, 64, v5
	v_and_b32_e32 v14, 24, v10
	s_barrier
; #define ATT_BAR() do { asm volatile("s_waitcnt lgkmcnt(0)" ::: "memory"); __builtin_amdgcn_s_barrier(); asm volatile("" ::: "memory"); } while (0)
; template <int DQK> __device__ __forceinline__ int kswz(int row, int colB) { return row * (DQK * 2) + (colB ^ kswz_x<DQK>(row)); }
; __device__ __forceinline__ int v_rd_base(int lane) { return ((lane & 3) << 3) | (((lane >> 2) & 3) << 6) | (((lane >> 4) & 1) << 5) | (((lane >> 5) & 1) << 8); }
; template <int MODE>
; __device__ __forceinline__ void attn_unit(unsigned char* ws_, const float* rpb, const float* sink, int l, int h, int qb, int kvq, unsigned char* lds_g) {
;     ...
; #pragma unroll
;   for (int i = 0; i < NCH; ++i) { const int X = (wid + 8 * i) * 1024 + lane * 16, row = X / (DQK * 2), cs = X % (DQK * 2), colB = cs ^ kswz_x<DQK>(row); kg[i] = (unsigned)(row * ldk + (colB >> 1)) * 2u; }
; #pragma unroll
;   for (int i = 0; i < 2; ++i) { const int X = (wid + 8 * i) * 1024 + lane * 16, st = X >> 9, w = X & 511, kk = ((st >> 2) << 3) | (w >> 6), c = ((st & 3) << 5) | ((w & 63) >> 1);
;     const int k = kk;
;     vg[i] = (unsigned)(k * ldv + c) * 2u; }
;   const int vb0 = (int)(uintptr_t)lds_g + v_rd_base(lane);
;   const int kbase0 = (int)(uintptr_t)lds_g + OFF_K;
;   constexpr int NKO = DQK == 192 ? 4 : ND;
;   int ko[NKO];
; #pragma unroll
;   for (int d0 = 0; d0 < NKO; ++d0) ko[d0] = kswz<DQK>(r32, (d0 * 16 + hi * 8) * 2);
;     ...
;   const int wslab = __builtin_amdgcn_readfirstlane(wid) * 1024;
;     ...
;   __syncthreads();
;   ATT_DMA(T0, 0); if (T0 + 1 < T1) { ATT_DMA(T0 + 1, 1); asm volatile("s_waitcnt vmcnt(%0)" :: "n"(NCH + 2) : "memory"); } else asm volatile("s_waitcnt vmcnt(0)" ::: "memory");
;   ATT_BAR();
;   int b = 0, bn = 2;
	global_load_lds_dwordx4 v2, s[4:5]
	s_add_i32 m0, s20, 0xe000
	v_or3_b32 v15, v14, v12, v13
	v_mul_u32_u24_e32 v17, 0x300, v17
	s_mul_i32 s27, s14, 0x300000
	global_load_lds_dwordx4 v4, s[4:5]
	s_add_i32 m0, s20, 0x10000
	v_or_b32_e32 v17, v17, v15
	v_mul_u32_u24_e32 v3, 0x300, v3
	global_load_lds_dwordx4 v6, s[4:5]
	s_add_u32 s4, s23, s27
	v_lshlrev_b32_e32 v17, 1, v17
	v_or_b32_e32 v3, v3, v15
	s_addc_u32 s5, s24, 0
	s_mov_b32 m0, s20
	v_lshlrev_b32_e32 v3, 1, v3
	global_load_lds_dwordx4 v17, s[4:5]
	s_add_i32 m0, s20, 0x2000
	s_or_b32 s25, s25, 64
	global_load_lds_dwordx4 v3, s[4:5]
	s_mul_i32 s4, s25, 0x900
	s_add_u32 s4, s21, s4
	s_addc_u32 s5, s22, 0
	s_add_i32 m0, s20, 0x12000
	s_mulk_i32 s25, 0x600
	global_load_lds_dwordx4 v2, s[4:5]
	s_add_i32 m0, s20, 0x14000
	v_lshlrev_b32_e32 v15, 1, v5
	global_load_lds_dwordx4 v4, s[4:5]
	s_add_i32 m0, s20, 0x16000
	v_lshlrev_b32_e32 v5, 3, v5
	global_load_lds_dwordx4 v6, s[4:5]
	s_add_u32 s4, s23, s25
	s_addc_u32 s5, s24, 0
	s_add_i32 m0, s20, 0x4000
	v_mul_u32_u24_e32 v19, 0x180, v177
	global_load_lds_dwordx4 v17, s[4:5]
	s_add_i32 m0, s20, 0x6000
	v_and_b32_e32 v5, 0x70, v5
	global_load_lds_dwordx4 v3, s[4:5]
	v_or_b32_e32 v3, 64, v0
	v_and_b32_e32 v10, 0x118, v10
	s_cmp_lg_u32 0, -1
	v_or_b32_e32 v20, 32, v0
	v_bitop3_b32 v181, v3, v19, v5 bitop3:0xde
	v_or_b32_e32 v3, 0x60, v0
	v_and_b32_e32 v9, 0xc0, v9
	v_cmp_gt_u32_e64 s[4:5], 32, v8
	s_cselect_b32 s22, 0, 0
	v_and_or_b32 v8, v15, 32, v10
	v_bitop3_b32 v149, v0, v19, v5 bitop3:0xde
	v_bitop3_b32 v180, v20, v19, v5 bitop3:0xde
	v_bitop3_b32 v183, v3, v19, v5 bitop3:0xde
	s_add_i32 s23, s22, 0xc080
	v_add3_u32 v200, v9, s22, v8
	v_lshrrev_b32_e32 v8, 3, v18
	v_add_u32_e32 v184, s23, v149
	v_add_u32_e32 v185, s23, v180
	v_add_u32_e32 v194, s23, v181
	v_add_u32_e32 v195, s23, v183
	s_add_i32 s23, s22, 0xc100
	v_mul_lo_u32 v8, v8, s30
	s_add_u32 s10, s27, s10
	v_mad_u32_u24 v8, v11, s31, v8
	s_addc_u32 s11, 0, s11
	v_or_b32_e32 v8, v8, v13
	s_add_u32 s10, s10, 0x17a58000
	v_or3_b32 v8, v8, v12, v14
	s_addc_u32 s11, s11, 0
	v_lshlrev_b32_e32 v8, 1, v8
	v_mov_b32_e32 v9, v1
	v_lshl_add_u64 v[150:151], s[10:11], 0, v[8:9]
	v_lshrrev_b32_e32 v8, 3, v16
	v_mul_lo_u32 v8, v8, s30
	v_mad_u32_u24 v8, v11, s31, v8
	s_add_u32 s8, s26, s8
	v_or_b32_e32 v8, v8, v13
	s_addc_u32 s9, 0, s9
	s_waitcnt vmcnt(5)
	v_or3_b32 v8, v8, v12, v14
	s_add_u32 s8, s8, 0x16870000
	v_mov_b32_e32 v3, v1
	v_mov_b32_e32 v5, v1
	v_mov_b32_e32 v7, v1
	s_waitcnt lgkmcnt(0)
	s_barrier
	v_lshlrev_b32_e32 v8, 1, v8
	s_addc_u32 s9, s9, 0
	v_mov_b32_e32 v16, v1
	v_mov_b32_e32 v17, v1
	v_lshl_add_u64 v[152:153], s[10:11], 0, v[8:9]
	v_lshl_add_u64 v[154:155], s[8:9], 0, v[6:7]
	v_lshl_add_u64 v[156:157], s[8:9], 0, v[4:5]
	v_lshl_add_u64 v[158:159], s[8:9], 0, v[2:3]
	v_mov_b32_e32 v2, v1
	v_mov_b32_e32 v4, v1
	v_mov_b32_e32 v6, v1
	v_mov_b32_e32 v8, v1
	v_mov_b32_e32 v10, v1
	v_mov_b32_e32 v11, v1
	v_mov_b32_e32 v12, v1
	v_mov_b32_e32 v13, v1
	v_mov_b32_e32 v14, v1
	v_mov_b32_e32 v15, v1
	v_mov_b64_e32 v[64:65], v[16:17]
	v_mov_b64_e32 v[48:49], v[16:17]
	v_mov_b64_e32 v[32:33], v[16:17]
	s_mov_b32 s17, 2
	v_ashrrev_i32_e32 v147, 31, v146
	v_lshl_add_u32 v182, v177, 2, v178
	s_mov_b32 s21, 0
	v_add_u32_e32 v196, s23, v149
	v_add_u32_e32 v197, s23, v180
	v_add_u32_e32 v198, s23, v181
	v_add_u32_e32 v199, s23, v183
	v_mov_b32_e32 v202, 0
	v_mov_b32_e32 v148, 0xefa18f08
	v_mov_b64_e32 v[62:63], v[14:15]
	v_mov_b64_e32 v[60:61], v[12:13]
	v_mov_b64_e32 v[58:59], v[10:11]
	v_mov_b64_e32 v[56:57], v[8:9]
	v_mov_b64_e32 v[54:55], v[6:7]
	v_mov_b64_e32 v[52:53], v[4:5]
	v_mov_b64_e32 v[50:51], v[2:3]
	v_mov_b64_e32 v[46:47], v[14:15]
	v_mov_b64_e32 v[44:45], v[12:13]
	v_mov_b64_e32 v[42:43], v[10:11]
	v_mov_b64_e32 v[40:41], v[8:9]
	v_mov_b64_e32 v[38:39], v[6:7]
	v_mov_b64_e32 v[36:37], v[4:5]
	v_mov_b64_e32 v[34:35], v[2:3]
	v_mov_b64_e32 v[30:31], v[14:15]
	v_mov_b64_e32 v[28:29], v[12:13]
	v_mov_b64_e32 v[26:27], v[10:11]
	v_mov_b64_e32 v[24:25], v[8:9]
	v_mov_b64_e32 v[22:23], v[6:7]
	v_mov_b64_e32 v[20:21], v[4:5]
	v_mov_b64_e32 v[18:19], v[2:3]
	s_mov_b32 s10, 0
	s_branch .LBB0_866
